# MLA loop variant P: 4-slot LDS ring, next tile's first K fragments read before the barrier, 4x unrolled; static s_setprio 1 for waves 4-7 in the MLA loop; early K(2)/V(1) loads in the unit prologue
# speedup vs baseline: 1.0614x; 1.0109x over previous
.LBB0_1037:
	v_cndmask_b32_e64 v1, 0, 1, s[0:1]
	v_cmp_ne_u32_e64 s[8:9], 1, v1
	s_andn2_b64 vcc, exec, s[0:1]
	s_cbranch_vccnz .LBB0_1039
	s_bitcmp1_b32 s28, 0
	s_cselect_b32 s30, 0x5800, 0
	v_add_u32_e32 v1, s30, v145
	ds_read_b128 v[2:5], v1
	ds_read_b128 v[150:153], v1 offset:6656
	ds_read_b128 v[154:157], v1 offset:32
	ds_read_b128 v[158:161], v1 offset:6688
	ds_read_b128 v[162:165], v1 offset:64
	ds_read_b128 v[166:169], v1 offset:6720
	ds_read_b128 v[170:173], v1 offset:96
	ds_read_b128 v[174:177], v1 offset:6752
	s_waitcnt lgkmcnt(7)
	v_mfma_f32_32x32x16_bf16 v[96:111], v[2:5], v[112:115], 0
	s_waitcnt lgkmcnt(6)
	v_mfma_f32_32x32x16_bf16 v[80:95], v[150:153], v[112:115], 0
	s_waitcnt lgkmcnt(5)
	v_mfma_f32_32x32x16_bf16 v[96:111], v[154:157], v[116:119], v[96:111]
	s_waitcnt lgkmcnt(4)
	v_mfma_f32_32x32x16_bf16 v[80:95], v[158:161], v[116:119], v[80:95]
	s_waitcnt lgkmcnt(3)
	v_mfma_f32_32x32x16_bf16 v[96:111], v[162:165], v[120:123], v[96:111]
	s_waitcnt lgkmcnt(2)
	v_mfma_f32_32x32x16_bf16 v[80:95], v[166:169], v[120:123], v[80:95]
	s_waitcnt lgkmcnt(1)
	v_mfma_f32_32x32x16_bf16 v[96:111], v[170:173], v[124:127], v[96:111]
	s_waitcnt lgkmcnt(0)
	v_mfma_f32_32x32x16_bf16 v[80:95], v[174:177], v[124:127], v[80:95]
	s_and_b64 vcc, exec, s[10:11]
	s_cbranch_vccz .LBB0_1040
	s_branch .LBB0_1041

.LBB0_1141:
	v_cndmask_b32_e64 v1, 0, 1, s[10:11]
	v_cmp_ne_u32_e64 s[6:7], 1, v1
	s_andn2_b64 vcc, exec, s[10:11]
	s_cbranch_vccnz .LBB0_1143
	s_bitcmp1_b32 s30, 0
	s_cselect_b32 s12, 0x5800, 0
	v_add_u32_e32 v1, s12, v224
	ds_read_b128 v[2:5], v1
	ds_read_b128 v[144:147], v1 offset:6656
	ds_read_b128 v[148:151], v1 offset:32
	ds_read_b128 v[152:155], v1 offset:6688
	ds_read_b128 v[156:159], v1 offset:64
	ds_read_b128 v[64:67], v1 offset:6720
	ds_read_b128 v[68:71], v1 offset:96
	ds_read_b128 v[72:75], v1 offset:6752
	s_waitcnt lgkmcnt(7)
	v_mfma_f32_32x32x16_bf16 v[16:31], v[2:5], v[176:179], v[80:95]
	s_waitcnt lgkmcnt(6)
	v_mfma_f32_32x32x16_bf16 v[48:63], v[144:147], v[176:179], v[80:95]
	s_waitcnt lgkmcnt(5)
	v_mfma_f32_32x32x16_bf16 v[16:31], v[148:151], v[180:183], v[16:31]
	s_waitcnt lgkmcnt(4)
	v_mfma_f32_32x32x16_bf16 v[48:63], v[152:155], v[180:183], v[48:63]
	s_waitcnt lgkmcnt(3)
	v_mfma_f32_32x32x16_bf16 v[16:31], v[156:159], v[184:187], v[16:31]
	s_waitcnt lgkmcnt(2)
	v_mfma_f32_32x32x16_bf16 v[48:63], v[64:67], v[184:187], v[48:63]
	s_waitcnt lgkmcnt(1)
	v_mfma_f32_32x32x16_bf16 v[16:31], v[68:71], v[188:191], v[16:31]
	s_waitcnt lgkmcnt(0)
	v_mfma_f32_32x32x16_bf16 v[48:63], v[72:75], v[188:191], v[48:63]
	s_branch .LBB0_1144

; #define LOADK(t) do { const int kp_ = TILE_KPOS(t); kreg = *(const u32x4*)((const char*)P.K + (size_t)(koff + (unsigned)(kp_ * KPITCH * 2))); if (VAR == 0 && tid < 256) pereg = *(const u32x4*)((const char*)P.KPE + (size_t)(peoff + (unsigned)(kp_ * 64))); } while (0)
; #define LOADV(t) do { const int kp_ = TILE_KPOS(t); vreg = *(const u32x4*)((const char*)P.VT + (size_t)(voff + (unsigned)(kp_ * 2))); } while (0)
; #define STOREK(buf) do { LAS unsigned char* kb_ = lds + (buf) * ABUF; *(LAS u32x4*)(kb_ + (tid >> 3) * KP + (tid & 7) * 16) = kreg; \
;         if (VAR == 0 && tid < 256) *(LAS u32x4*)(kb_ + (tid >> 2) * KP + 128 + (tid & 3) * 16) = pereg; } while (0)
; #define STOREV(buf) do { *(LAS u32x4*)(lds + (buf) * ABUF + KT_BYTES + (tid >> 3) * VP + (tid & 7) * 16) = vreg; } while (0)
; template <int VAR>
; __device__ __forceinline__ void attn_phase(LAS unsigned char* lds, const AttnP P, int vcu, int G, int wave_s) {
;     ...
;         const int rot = (VAR == 0 && !isctx) ? ((vcu & 31) * 4 + (vcu >> 5)) % 132 : 0;
;         int na_rs = 0; if (VAR == 2) { na_rs = p_b - 4; na_rs = na_rs < 0 ? 0 : (na_rs > 120 ? 120 : na_rs); }
;         LOADK(0); LOADV(0); STOREK(0); STOREV(0);
;         if (nt > 1) { LOADK(1); STOREK(1); }
;         __syncthreads();
;         f32x16 pc0, pc1; const f32x16 zero16 = {};
;         QK_TILE(pc0, pc1, 0, zero16);
;         float mref = rowmax32(pc0, pc1), lrun = 0.f;
;         if (VAR == 1) { const float sk = P.sink[hq] * LOG2E; mref = __builtin_fmaxf(mref, sk); lrun = (hi == 0) ? __builtin_amdgcn_exp2f(sk - mref) : 0.f; }
;         f32x16 negm = {};
;         if (USE_NEGM) {
; #pragma unroll
;             for (int r = 0; r < 16; ++r) { pc0[r] -= mref; pc1[r] -= mref; negm[r] = -mref; }
;         }
;         float rmc = 0.f;
;         bool need_c = true;
;         __syncthreads();
;         for (int t = 0; t < nt; ++t) {
;             const bool hn = (t + 1 < nt);
;             if (hn) { const int t2 = (t + 2 < nt) ? t + 2 : nt - 1; LOADK(t2); LOADV(t + 1); }
.LBB0_1173:
	s_or_b64 exec, exec, s[0:1]
	s_waitcnt vmcnt(0)
	ds_write_b128 v172, v[2:5] offset:22528
	s_and_saveexec_b64 s[0:1], s[2:3]
	ds_write_b128 v176, v[138:141] offset:22656
	s_or_b64 exec, exec, s[0:1]
	s_waitcnt lgkmcnt(0)
	s_barrier
	s_add_i32 s19, s9, -1
	s_min_u32 s0, s19, 2
	s_add_i32 s0, s0, s10
	s_cmp_ge_i32 s0, s9
	s_cselect_b32 s1, s9, 0
	s_sub_i32 s13, s0, s1
	s_add_i32 s0, s10, 1
	s_cmp_ge_i32 s0, s9
	s_cselect_b32 s1, s9, 0
	s_sub_i32 s19, s0, s1
	s_and_saveexec_b64 s[0:1], s[2:3]
	s_cbranch_execz .Lmla_early_nope
	v_lshl_add_u32 v222, s13, 12, v179
	global_load_dwordx4 v[138:141], v222, s[62:63]
.Lmla_early_nope:
	s_or_b64 exec, exec, s[0:1]
	v_lshl_add_u32 v222, s13, 17, v178
	global_load_dwordx4 v[146:149], v222, s[52:53]
	s_movk_i32 s0, 0x4200
	v_mul_lo_u32 v223, v1, s0
	v_add_u32_e32 v223, v223, v171
	s_lshl_b32 s0, s19, 7
	s_addk_i32 s0, 0xff80
	v_add_u32_e32 v222, s0, v223
	global_load_dwordx4 v[142:145], v222, s[56:57]
	ds_read_b128 v[2:5], v174
	ds_read_b128 v[6:9], v174 offset:32
	s_waitcnt lgkmcnt(1)
	v_mfma_f32_32x32x16_bf16 v[34:49], v[2:5], v[114:117], 0
	ds_read_b128 v[2:5], v174 offset:6656
	ds_read_b128 v[10:13], v174 offset:6688
	v_readlane_b32 s36, v255, 18
	s_mov_b32 s0, s36
	v_readlane_b32 s37, v255, 19
	v_readlane_b32 s38, v255, 20
	v_readlane_b32 s39, v255, 21
	v_readlane_b32 s40, v255, 22
	s_waitcnt lgkmcnt(2)
	v_mfma_f32_32x32x16_bf16 v[34:49], v[6:9], v[118:121], v[34:49]
	v_readlane_b32 s41, v255, 23
	v_readlane_b32 s42, v255, 24
	v_readlane_b32 s43, v255, 25
	v_readlane_b32 s44, v255, 26
	v_readlane_b32 s45, v255, 27
	v_readlane_b32 s46, v255, 28
	v_readlane_b32 s47, v255, 29
	s_waitcnt lgkmcnt(1)
	v_mfma_f32_32x32x16_bf16 v[18:33], v[2:5], v[114:117], 0
	ds_read_b128 v[2:5], v174 offset:64
	ds_read_b128 v[6:9], v174 offset:96
	v_readlane_b32 s48, v255, 30
	v_readlane_b32 s49, v255, 31
	v_readlane_b32 s50, v255, 32
	v_readlane_b32 s51, v255, 33
	v_writelane_b32 v255, s0, 18
	s_mov_b32 s37, s36
	s_waitcnt lgkmcnt(1)
	v_mfma_f32_32x32x16_bf16 v[34:49], v[2:5], v[122:125], v[34:49]
	v_writelane_b32 v255, s1, 19
	v_writelane_b32 v255, s2, 20
	v_writelane_b32 v255, s3, 21
	v_writelane_b32 v255, s4, 22
	v_writelane_b32 v255, s5, 23
	v_writelane_b32 v255, s6, 24
	v_writelane_b32 v255, s7, 25
	v_mfma_f32_32x32x16_bf16 v[18:33], v[10:13], v[118:121], v[18:33]
	ds_read_b128 v[2:5], v174 offset:6720
	ds_read_b128 v[10:13], v174 offset:6752
	v_writelane_b32 v255, s8, 26
	v_writelane_b32 v255, s9, 27
	v_writelane_b32 v255, s10, 28
	v_writelane_b32 v255, s11, 29
	v_writelane_b32 v255, s12, 30
	v_writelane_b32 v255, s13, 31
	s_waitcnt lgkmcnt(2)
	v_mfma_f32_32x32x16_bf16 v[34:49], v[6:9], v[126:129], v[34:49]
	v_writelane_b32 v255, s14, 32
	s_mov_b32 s38, s36
	s_mov_b32 s39, s36
	s_mov_b32 s40, s36
	s_mov_b32 s41, s36
	s_mov_b32 s42, s36
	s_mov_b32 s43, s36
	s_waitcnt lgkmcnt(1)
	v_mfma_f32_32x32x16_bf16 v[18:33], v[2:5], v[122:125], v[18:33]
	ds_read_b128 v[2:5], v174 offset:128
	ds_read_b128 v[6:9], v174 offset:160
	ds_read_b128 v[50:53], v174 offset:6816
	s_mov_b32 s44, s36
	s_mov_b32 s45, s36
	s_mov_b32 s46, s36
	s_mov_b32 s47, s36
	s_mov_b32 s48, s36
	s_waitcnt lgkmcnt(2)
	v_mfma_f32_32x32x16_bf16 v[34:49], v[2:5], v[130:133], v[34:49]
	ds_read_b128 v[2:5], v174 offset:6784
	s_mov_b32 s49, s36
	s_mov_b32 s50, s36
	s_mov_b32 s51, s36
	v_writelane_b32 v255, s15, 33
	s_movk_i32 s0, 0x4200
	v_mul_lo_u32 v1, v1, s0
	v_mfma_f32_32x32x16_bf16 v[18:33], v[10:13], v[126:129], v[18:33]
	v_or_b32_e32 v1, v171, v1
	s_add_i32 s12, s9, -1
	v_lshl_add_u32 v181, s10, 7, v1
	v_mov_b32_e32 v1, 0
	s_mov_b32 s11, 1
	v_mov_b32_e32 v82, 0
	s_waitcnt lgkmcnt(0)
	v_mfma_f32_32x32x16_bf16 v[18:33], v[2:5], v[130:133], v[18:33]
	s_barrier
	v_mfma_f32_32x32x16_bf16 v[34:49], v[6:9], v[134:137], v[34:49]
	v_mov_b64_e32 v[2:3], s[36:37]
	v_mov_b64_e32 v[16:17], s[50:51]
	v_mov_b64_e32 v[4:5], s[38:39]
	v_mov_b64_e32 v[6:7], s[40:41]
	v_mov_b64_e32 v[8:9], s[42:43]
	v_mov_b64_e32 v[10:11], s[44:45]
	v_mov_b64_e32 v[12:13], s[46:47]
	v_mfma_f32_32x32x16_bf16 v[18:33], v[50:53], v[134:137], v[18:33]
	s_nop 3
	v_max_f32_e32 v54, v35, v35
	v_max_f32_e32 v55, v34, v34
	v_max_f32_e32 v54, v55, v54
	v_mov_b64_e32 v[14:15], s[48:49]
	s_nop 3
	v_max3_f32 v50, v36, v37, v19
	v_max3_f32 v51, v54, v18, v20
	v_max3_f32 v51, v51, v21, v38
	v_max3_f32 v50, v50, v40, v41
	v_max3_f32 v51, v51, v39, v22
	v_max3_f32 v50, v50, v24, v25
	v_max3_f32 v51, v51, v23, v42
	v_max3_f32 v50, v50, v44, v45
	v_max3_f32 v51, v51, v43, v26
	v_max3_f32 v50, v50, v28, v29
	v_max3_f32 v51, v51, v27, v46
	v_max3_f32 v50, v50, v48, v49
	v_max3_f32 v51, v51, v47, v30
	v_max3_f32 v50, v50, v32, v33
	v_max3_f32 v50, v51, v31, v50
	v_mov_b32_e32 v51, v50
	s_nop 1
	v_permlane32_swap_b32_e32 v50, v51
	v_max_f32_e32 v51, v51, v51
	v_max_f32_e32 v50, v50, v50
	v_max_f32_e32 v180, v50, v51
	v_xor_b32_e32 v66, 0x80000000, v180
	v_sub_f32_e32 v65, v33, v180
	v_sub_f32_e32 v64, v32, v180
	v_sub_f32_e32 v63, v31, v180
	v_sub_f32_e32 v62, v30, v180
	v_sub_f32_e32 v61, v29, v180
	v_sub_f32_e32 v60, v28, v180
	v_sub_f32_e32 v59, v27, v180
	v_sub_f32_e32 v58, v26, v180
	v_sub_f32_e32 v57, v25, v180
	v_sub_f32_e32 v56, v24, v180
	v_sub_f32_e32 v55, v23, v180
	v_sub_f32_e32 v54, v22, v180
	v_sub_f32_e32 v53, v21, v180
	v_sub_f32_e32 v52, v20, v180
	v_sub_f32_e32 v51, v19, v180
	v_sub_f32_e32 v50, v18, v180
	v_mov_b64_e32 v[32:33], v[16:17]
	v_sub_f32_e32 v49, v49, v180
	v_sub_f32_e32 v48, v48, v180
	v_sub_f32_e32 v47, v47, v180
	v_sub_f32_e32 v46, v46, v180
	v_sub_f32_e32 v45, v45, v180
	v_sub_f32_e32 v44, v44, v180
	v_sub_f32_e32 v43, v43, v180
	v_sub_f32_e32 v42, v42, v180
	v_sub_f32_e32 v41, v41, v180
	v_sub_f32_e32 v40, v40, v180
	v_sub_f32_e32 v39, v39, v180
	v_sub_f32_e32 v38, v38, v180
	v_sub_f32_e32 v37, v37, v180
	v_sub_f32_e32 v36, v36, v180
	v_sub_f32_e32 v35, v35, v180
	v_sub_f32_e32 v34, v34, v180
	v_mov_b64_e32 v[30:31], v[14:15]
	v_mov_b64_e32 v[28:29], v[12:13]
	v_mov_b64_e32 v[26:27], v[10:11]
	v_mov_b64_e32 v[24:25], v[8:9]
	v_mov_b64_e32 v[22:23], v[6:7]
	v_mov_b64_e32 v[20:21], v[4:5]
	v_mov_b64_e32 v[18:19], v[2:3]
	v_mov_b32_e32 v67, v66
	v_mov_b32_e32 v68, v66
	v_mov_b32_e32 v69, v66
	v_mov_b32_e32 v70, v66
	v_mov_b32_e32 v71, v66
	v_mov_b32_e32 v72, v66
	v_mov_b32_e32 v73, v66
	v_mov_b32_e32 v74, v66
	v_mov_b32_e32 v75, v66
	v_mov_b32_e32 v76, v66
	v_mov_b32_e32 v77, v66
	v_mov_b32_e32 v78, v66
	v_mov_b32_e32 v79, v66
	v_mov_b32_e32 v80, v66
	v_mov_b32_e32 v81, v66
	v_add_u32_e32 v228, v166, v165
	v_mov_b32_e32 v167, v82
	s_add_i32 s0, s10, 1
	s_lshl_b32 s0, s0, 7
	v_subrev_u32_e32 v168, s0, v181
	v_add_u32_e32 v229, 0xb000, v174
	v_add_u32_e32 v181, 0xb000, v228
	s_waitcnt vmcnt(0)
; #define LOADK(t) do { const int kp_ = TILE_KPOS(t); kreg = *(const u32x4*)((const char*)P.K + (size_t)(koff + (unsigned)(kp_ * KPITCH * 2))); if (VAR == 0 && tid < 256) pereg = *(const u32x4*)((const char*)P.KPE + (size_t)(peoff + (unsigned)(kp_ * 64))); } while (0)
; #define LOADV(t) do { const int kp_ = TILE_KPOS(t); vreg = *(const u32x4*)((const char*)P.VT + (size_t)(voff + (unsigned)(kp_ * 2))); } while (0)
; #define STOREK(buf) do { LAS unsigned char* kb_ = lds + (buf) * ABUF; *(LAS u32x4*)(kb_ + (tid >> 3) * KP + (tid & 7) * 16) = kreg; \
;         if (VAR == 0 && tid < 256) *(LAS u32x4*)(kb_ + (tid >> 2) * KP + 128 + (tid & 3) * 16) = pereg; } while (0)
; #define STOREV(buf) do { *(LAS u32x4*)(lds + (buf) * ABUF + KT_BYTES + (tid >> 3) * VP + (tid & 7) * 16) = vreg; } while (0)
; template <int VAR>
; __device__ __forceinline__ void attn_phase(LAS unsigned char* lds, const AttnP P, int vcu, int G, int wave_s) {
;     ...
;         LOADK(0); LOADV(0); STOREK(0); STOREV(0);
;         if (nt > 1) { LOADK(1); STOREK(1); }
;         __syncthreads();
;         f32x16 pc0, pc1; const f32x16 zero16 = {};
;         QK_TILE(pc0, pc1, 0, zero16);
;         float mref = rowmax32(pc0, pc1), lrun = 0.f;
;         if (VAR == 1) { const float sk = P.sink[hq] * LOG2E; mref = __builtin_fmaxf(mref, sk); lrun = (hi == 0) ? __builtin_amdgcn_exp2f(sk - mref) : 0.f; }
;         f32x16 negm = {};
;         if (USE_NEGM) {
; #pragma unroll
;             for (int r = 0; r < 16; ++r) { pc0[r] -= mref; pc1[r] -= mref; negm[r] = -mref; }
;         }
;         float rmc = 0.f;
;         bool need_c = true;
;         __syncthreads();
;         for (int t = 0; t < nt; ++t) {
;             const bool hn = (t + 1 < nt);
;             if (hn) { const int t2 = (t + 2 < nt) ? t + 2 : nt - 1; LOADK(t2); LOADV(t + 1); }
;             const bool need_n = hn && NEED(t + 1);
	s_and_saveexec_b64 s[0:1], s[2:3]
	ds_write_b128 v176, v[138:141] offset:45184
	s_or_b64 exec, exec, s[0:1]
	ds_write_b128 v172, v[146:149] offset:45056
	ds_write_b128 v173, v[142:145] offset:35840
	s_add_i32 s0, s11, 2
	s_min_u32 s0, s0, s12
	s_add_i32 s0, s0, s10
	s_cmp_ge_i32 s0, s9
	s_cselect_b32 s1, s9, 0
	s_sub_i32 s19, s0, s1
	s_add_i32 s0, s11, 1
	s_min_u32 s0, s0, s12
	s_add_i32 s0, s0, s10
	s_cmp_ge_i32 s0, s9
	s_cselect_b32 s1, s9, 0
	s_sub_i32 s13, s0, s1
	s_and_saveexec_b64 s[0:1], s[2:3]
	s_cbranch_execz .Lmla_pre0
	v_lshl_add_u32 v222, s19, 12, v179
	global_load_dwordx4 v[138:141], v222, s[62:63]
.Lmla_pre0:
	s_or_b64 exec, exec, s[0:1]
	v_lshl_add_u32 v222, s19, 17, v178
	global_load_dwordx4 v[146:149], v222, s[52:53]
	v_lshl_add_u32 v222, s13, 7, v168
	global_load_dwordx4 v[142:145], v222, s[56:57]
	s_add_i32 s0, s11, 3
	s_min_u32 s0, s0, s12
	s_add_i32 s0, s0, s10
	s_cmp_ge_i32 s0, s9
	s_cselect_b32 s1, s9, 0
	s_sub_i32 s19, s0, s1
	s_add_i32 s0, s11, 2
	s_min_u32 s0, s0, s12
	s_add_i32 s0, s0, s10
	s_cmp_ge_i32 s0, s9
	s_cselect_b32 s1, s9, 0
	s_sub_i32 s13, s0, s1
	s_and_saveexec_b64 s[0:1], s[2:3]
	s_cbranch_execz .Lmla_pre1
	v_lshl_add_u32 v222, s19, 12, v179
	global_load_dwordx4 v[160:163], v222, s[62:63]
.Lmla_pre1:
	s_or_b64 exec, exec, s[0:1]
	v_lshl_add_u32 v222, s19, 17, v178
	global_load_dwordx4 v[150:153], v222, s[52:53]
	v_lshl_add_u32 v222, s13, 7, v168
	global_load_dwordx4 v[202:205], v222, s[56:57]
	s_and_b64 vcc, exec, s[2:3]
	s_cbranch_vccnz .Lmla_noprio
	s_setprio 1
.Lmla_noprio:
	s_waitcnt lgkmcnt(0)
	s_barrier
	ds_read_b128 v[182:185], v174 offset:22528
	ds_read_b128 v[186:189], v174 offset:29184
	ds_read_b128 v[190:193], v174 offset:22560
	ds_read_b128 v[194:197], v174 offset:29216
.Lmla_p0:
	v_cmp_lt_f32_e32 vcc, s66, v167
	s_cbranch_vccnz .Lmla_p0_resc
; template <int VAR>
; __device__ __forceinline__ void attn_phase(LAS unsigned char* lds, const AttnP P, int vcu, int G, int wave_s) {
;     ...
;                 if (ND0 == 6) {
;                     KR1(0); KR1(1); KR1(2); KR1(3); SB();
;                     QK1(0, negm); EX2(pc0, 0, w0.x); KR1(4); SB();
;                     QK1(1, negm); EX2(pc0, 2, w0.y); KR1(5); SB();
;                     QK1(2, pn0); EX2(pc0, 4, w0.z); KR1(6); SB();
;                     QK1(3, pn1); EX2(pc0, 6, w0.w); KR1(7); SB();
;                     QK1(4, pn0); EX2(pc0, 8, w1.x); KR1(8); SB();
;                     QK1(5, pn1); EX2(pc0, 10, w1.y); KR1(9); SB();
;                     QK1(6, pn0); EX2(pc0, 12, w1.z); KR1(10); SB();
;                     QK1(7, pn1); EX2(pc0, 14, w1.w); KR1(11); SB();
;                     QK1(8, pn0); EX2(pc1, 0, w2.x); VR1(0); SB();
;                     QK1(9, pn1); EX2(pc1, 2, w2.y); VR1(1); SB();
;                     QK1(10, pn0); EX2(pc1, 4, w2.z); VR1(2); SB();
;                     QK1(11, pn1); EX2(pc1, 6, w2.w); VR1(3); SB();
;                 } else {
;                     KR1(0); KR1(1); KR1(2); KR1(3); SB();
;                     QK1(0, negm); EX2(pc0, 0, w0.x); EX2(pc0, 2, w0.y); KR1(4); SB();
;                     QK1(1, negm); EX2(pc0, 4, w0.z); EX2(pc0, 6, w0.w); KR1(5); SB();
;                     QK1(2, pn0); EX2(pc0, 8, w1.x); EX2(pc0, 10, w1.y); KR1(6); SB();
;                     QK1(3, pn1); EX2(pc0, 12, w1.z); EX2(pc0, 14, w1.w); KR1(7); SB();
;                     QK1(4, pn0); EX2(pc1, 0, w2.x); VR1(0); SB();
;                     QK1(5, pn1); EX2(pc1, 2, w2.y); VR1(1); SB();
;                     QK1(6, pn0); EX2(pc1, 4, w2.z); VR1(2); SB();
;                     QK1(7, pn1); EX2(pc1, 6, w2.w); VR1(3); SB();
;                 }
;                 PV1(0, w0); EX2(pc1, 8, w3.x); VR1(4); SB();
;                 PV1(1, w0); EX2(pc1, 10, w3.y); VR1(5); SB();
;                 PV1(2, w1); EX2(pc1, 12, w3.z); VR1(6); SB();
;                 PV1(3, w1); EX2(pc1, 14, w3.w); VR1(7); SB();
;                 lrun += sacc;
;                 PV1(4, w2); MASK_TILE(pn0, pn1, t + 1); SB();
;                 PV1(5, w2); SB();
;                 PV1(6, w3); SB();
;                 PV1(7, w3); rmn = rowmax32(pn0, pn1); if (!USE_NEGM) rmn -= mref; SB();
;     ...
;             if (hn) { STOREK(t & 1); STOREV((t + 1) & 1); }
;             __syncthreads();
.Lmla_p0_go:
	v_exp_f32_e32 v222, v34
	v_exp_f32_e32 v223, v35
	v_add_f32_e32 v164, 0, v222
	v_cvt_pk_bf16_f32 v206, v222, v223
	v_add_f32_e32 v164, v223, v164
	v_exp_f32_e32 v224, v36
	v_exp_f32_e32 v225, v37
	v_add_f32_e32 v164, v224, v164
	v_cvt_pk_bf16_f32 v207, v224, v225
	v_add_f32_e32 v164, v225, v164
	s_waitcnt lgkmcnt(3)
	v_mfma_f32_32x32x16_bf16 v[82:97], v[182:185], v[114:117], v[66:81]
	ds_read_b128 v[198:201], v174 offset:22592
	v_exp_f32_e32 v222, v38
	v_exp_f32_e32 v223, v39
	v_add_f32_e32 v164, v222, v164
	v_cvt_pk_bf16_f32 v208, v222, v223
	v_add_f32_e32 v164, v223, v164
	s_waitcnt lgkmcnt(3)
	v_mfma_f32_32x32x16_bf16 v[98:113], v[186:189], v[114:117], v[66:81]
	ds_read_b128 v[182:185], v174 offset:29248
	v_exp_f32_e32 v224, v40
	v_exp_f32_e32 v225, v41
	v_add_f32_e32 v164, v224, v164
	v_cvt_pk_bf16_f32 v209, v224, v225
	v_add_f32_e32 v164, v225, v164
	s_waitcnt lgkmcnt(3)
	v_mfma_f32_32x32x16_bf16 v[82:97], v[190:193], v[118:121], v[82:97]
	ds_read_b128 v[186:189], v174 offset:22624
	v_exp_f32_e32 v222, v42
	v_exp_f32_e32 v223, v43
	v_add_f32_e32 v164, v222, v164
	v_cvt_pk_bf16_f32 v210, v222, v223
	v_add_f32_e32 v164, v223, v164
	s_waitcnt lgkmcnt(3)
	v_mfma_f32_32x32x16_bf16 v[98:113], v[194:197], v[118:121], v[98:113]
	ds_read_b128 v[190:193], v174 offset:29280
	v_exp_f32_e32 v224, v44
	v_exp_f32_e32 v225, v45
	v_add_f32_e32 v164, v224, v164
	v_cvt_pk_bf16_f32 v211, v224, v225
	v_add_f32_e32 v164, v225, v164
	s_waitcnt lgkmcnt(3)
	v_mfma_f32_32x32x16_bf16 v[82:97], v[198:201], v[122:125], v[82:97]
	ds_read_b128 v[194:197], v174 offset:22656
	v_exp_f32_e32 v222, v46
	v_exp_f32_e32 v223, v47
	v_add_f32_e32 v164, v222, v164
	v_cvt_pk_bf16_f32 v212, v222, v223
	v_add_f32_e32 v164, v223, v164
	s_waitcnt lgkmcnt(3)
	v_mfma_f32_32x32x16_bf16 v[98:113], v[182:185], v[122:125], v[98:113]
	ds_read_b128 v[198:201], v174 offset:29312
	v_exp_f32_e32 v224, v48
	v_exp_f32_e32 v225, v49
	v_add_f32_e32 v164, v224, v164
	v_cvt_pk_bf16_f32 v213, v224, v225
	v_add_f32_e32 v164, v225, v164
	s_waitcnt lgkmcnt(3)
	v_mfma_f32_32x32x16_bf16 v[82:97], v[186:189], v[126:129], v[82:97]
	ds_read_b128 v[182:185], v174 offset:22688
	v_exp_f32_e32 v222, v50
	v_exp_f32_e32 v223, v51
	v_add_f32_e32 v164, v222, v164
	v_cvt_pk_bf16_f32 v214, v222, v223
	v_add_f32_e32 v164, v223, v164
	s_waitcnt lgkmcnt(3)
	v_mfma_f32_32x32x16_bf16 v[98:113], v[190:193], v[126:129], v[98:113]
	ds_read_b128 v[186:189], v174 offset:29344
	v_exp_f32_e32 v224, v52
	v_exp_f32_e32 v225, v53
	v_add_f32_e32 v164, v224, v164
	v_cvt_pk_bf16_f32 v215, v224, v225
	v_add_f32_e32 v164, v225, v164
	s_waitcnt lgkmcnt(3)
	v_mfma_f32_32x32x16_bf16 v[82:97], v[194:197], v[130:133], v[82:97]
	ds_read_b128 v[190:193], v228 offset:13312
	v_exp_f32_e32 v222, v54
	v_exp_f32_e32 v223, v55
	v_add_f32_e32 v164, v222, v164
	v_cvt_pk_bf16_f32 v216, v222, v223
	v_add_f32_e32 v164, v223, v164
	s_waitcnt lgkmcnt(3)
	v_mfma_f32_32x32x16_bf16 v[98:113], v[198:201], v[130:133], v[98:113]
	ds_read_b128 v[194:197], v228 offset:17920
	v_exp_f32_e32 v224, v56
	v_exp_f32_e32 v225, v57
	v_add_f32_e32 v164, v224, v164
	v_cvt_pk_bf16_f32 v217, v224, v225
	v_add_f32_e32 v164, v225, v164
	s_waitcnt lgkmcnt(3)
	v_mfma_f32_32x32x16_bf16 v[82:97], v[182:185], v[134:137], v[82:97]
	ds_read_b128 v[198:201], v228 offset:13344
	v_exp_f32_e32 v222, v58
	v_exp_f32_e32 v223, v59
	v_add_f32_e32 v164, v222, v164
	v_cvt_pk_bf16_f32 v218, v222, v223
	v_add_f32_e32 v164, v223, v164
	s_waitcnt lgkmcnt(3)
	v_mfma_f32_32x32x16_bf16 v[98:113], v[186:189], v[134:137], v[98:113]
	ds_read_b128 v[182:185], v228 offset:17952
	v_exp_f32_e32 v224, v60
	v_exp_f32_e32 v225, v61
	v_add_f32_e32 v164, v224, v164
	v_cvt_pk_bf16_f32 v219, v224, v225
	v_add_f32_e32 v164, v225, v164
	s_waitcnt lgkmcnt(3)
	v_mfma_f32_32x32x16_bf16 v[2:17], v[190:193], v[206:209], v[2:17]
	ds_read_b128 v[186:189], v228 offset:13376
	v_exp_f32_e32 v222, v62
	v_exp_f32_e32 v223, v63
	v_add_f32_e32 v164, v222, v164
	v_cvt_pk_bf16_f32 v220, v222, v223
	v_add_f32_e32 v164, v223, v164
	s_waitcnt lgkmcnt(3)
	v_mfma_f32_32x32x16_bf16 v[18:33], v[194:197], v[206:209], v[18:33]
	ds_read_b128 v[190:193], v228 offset:17984
	v_exp_f32_e32 v224, v64
	v_exp_f32_e32 v225, v65
	v_add_f32_e32 v164, v224, v164
	v_cvt_pk_bf16_f32 v221, v224, v225
	v_add_f32_e32 v164, v225, v164
	s_waitcnt lgkmcnt(3)
	v_mfma_f32_32x32x16_bf16 v[2:17], v[198:201], v[210:213], v[2:17]
	ds_read_b128 v[194:197], v228 offset:13408
	v_max3_f32 v224, v82, v83, v84
	v_max3_f32 v225, v98, v99, v100
	v_max3_f32 v224, v224, v85, v86
	s_waitcnt lgkmcnt(3)
	v_mfma_f32_32x32x16_bf16 v[18:33], v[182:185], v[210:213], v[18:33]
	ds_read_b128 v[198:201], v228 offset:18016
	v_max3_f32 v225, v225, v101, v102
	v_max3_f32 v224, v224, v87, v88
	v_max3_f32 v225, v225, v103, v104
	s_waitcnt lgkmcnt(3)
	v_mfma_f32_32x32x16_bf16 v[2:17], v[186:189], v[214:217], v[2:17]
	ds_read_b128 v[182:185], v229
	v_max3_f32 v224, v224, v89, v90
	v_max3_f32 v225, v225, v105, v106
	v_max3_f32 v224, v224, v91, v92
	s_add_i32 s0, s11, 4
	s_min_u32 s0, s0, s12
	s_add_i32 s0, s0, s10
	s_cmp_ge_i32 s0, s9
	s_cselect_b32 s1, s9, 0
	s_sub_i32 s19, s0, s1
	s_add_i32 s0, s11, 3
	s_min_u32 s0, s0, s12
	s_add_i32 s0, s0, s10
	s_cmp_ge_i32 s0, s9
	s_cselect_b32 s1, s9, 0
	s_sub_i32 s13, s0, s1
	s_waitcnt lgkmcnt(3)
	v_mfma_f32_32x32x16_bf16 v[18:33], v[190:193], v[214:217], v[18:33]
	ds_read_b128 v[186:189], v229 offset:6656
	v_max3_f32 v225, v225, v107, v108
	v_max3_f32 v224, v224, v93, v94
	v_max3_f32 v225, v225, v109, v110
	s_and_b64 vcc, exec, s[2:3]
	s_cbranch_vccz .Lmla_p0_w47
	s_waitcnt vmcnt(3)
	v_add_u32_e32 v222, 0xb000, v176
	ds_write_b128 v222, v[138:141] offset:22656
	v_add_u32_e32 v222, 0xb000, v172
	ds_write_b128 v222, v[146:149] offset:22528
	ds_write_b128 v173, v[142:145] offset:58368
	v_lshl_add_u32 v222, s19, 12, v179
	global_load_dwordx4 v[138:141], v222, s[62:63]
	v_lshl_add_u32 v222, s19, 17, v178
	global_load_dwordx4 v[146:149], v222, s[52:53]
	v_lshl_add_u32 v222, s13, 7, v168
	global_load_dwordx4 v[142:145], v222, s[56:57]
	s_branch .Lmla_p0_join
.Lmla_p0_w47:
	s_waitcnt vmcnt(2)
	v_add_u32_e32 v222, 0xb000, v172
	ds_write_b128 v222, v[146:149] offset:22528
	ds_write_b128 v173, v[142:145] offset:58368
	v_lshl_add_u32 v222, s19, 17, v178
	global_load_dwordx4 v[146:149], v222, s[52:53]
	v_lshl_add_u32 v222, s13, 7, v168
	global_load_dwordx4 v[142:145], v222, s[56:57]
.Lmla_p0_join:
	s_waitcnt lgkmcnt(5)
	v_mfma_f32_32x32x16_bf16 v[2:17], v[194:197], v[218:221], v[2:17]
	ds_read_b128 v[190:193], v229 offset:32
	v_max3_f32 v224, v224, v95, v96
	v_max3_f32 v225, v225, v111, v112
	s_waitcnt lgkmcnt(5)
	v_mfma_f32_32x32x16_bf16 v[18:33], v[198:201], v[218:221], v[18:33]
	ds_read_b128 v[194:197], v229 offset:6688
	v_max3_f32 v224, v224, v97, v113
	v_max_f32_e32 v224, v224, v225
	v_mov_b32_e32 v225, v224
	v_add_f32_e32 v1, v1, v164
	s_add_i32 s11, s11, 1
	s_nop 0
	v_permlane32_swap_b32_e32 v224, v225
	s_cmp_eq_u32 s9, s11
	v_max_f32_e32 v167, v224, v225
	s_waitcnt lgkmcnt(2)
	s_barrier
	s_cbranch_scc1 .Lmla_exit_p0

; template <int VAR>
; __device__ __forceinline__ void attn_phase(LAS unsigned char* lds, const AttnP P, int vcu, int G, int wave_s) {
;     ...
;                 if (ND0 == 6) {
;                     KR1(0); KR1(1); KR1(2); KR1(3); SB();
;                     QK1(0, negm); EX2(pc0, 0, w0.x); KR1(4); SB();
;                     QK1(1, negm); EX2(pc0, 2, w0.y); KR1(5); SB();
;                     QK1(2, pn0); EX2(pc0, 4, w0.z); KR1(6); SB();
;                     QK1(3, pn1); EX2(pc0, 6, w0.w); KR1(7); SB();
;                     QK1(4, pn0); EX2(pc0, 8, w1.x); KR1(8); SB();
;                     QK1(5, pn1); EX2(pc0, 10, w1.y); KR1(9); SB();
;                     QK1(6, pn0); EX2(pc0, 12, w1.z); KR1(10); SB();
;                     QK1(7, pn1); EX2(pc0, 14, w1.w); KR1(11); SB();
;                     QK1(8, pn0); EX2(pc1, 0, w2.x); VR1(0); SB();
;                     QK1(9, pn1); EX2(pc1, 2, w2.y); VR1(1); SB();
;                     QK1(10, pn0); EX2(pc1, 4, w2.z); VR1(2); SB();
;                     QK1(11, pn1); EX2(pc1, 6, w2.w); VR1(3); SB();
;                 } else {
;                     KR1(0); KR1(1); KR1(2); KR1(3); SB();
;                     QK1(0, negm); EX2(pc0, 0, w0.x); EX2(pc0, 2, w0.y); KR1(4); SB();
;                     QK1(1, negm); EX2(pc0, 4, w0.z); EX2(pc0, 6, w0.w); KR1(5); SB();
;                     QK1(2, pn0); EX2(pc0, 8, w1.x); EX2(pc0, 10, w1.y); KR1(6); SB();
;                     QK1(3, pn1); EX2(pc0, 12, w1.z); EX2(pc0, 14, w1.w); KR1(7); SB();
;                     QK1(4, pn0); EX2(pc1, 0, w2.x); VR1(0); SB();
;                     QK1(5, pn1); EX2(pc1, 2, w2.y); VR1(1); SB();
;                     QK1(6, pn0); EX2(pc1, 4, w2.z); VR1(2); SB();
;                     QK1(7, pn1); EX2(pc1, 6, w2.w); VR1(3); SB();
;                 }
;                 PV1(0, w0); EX2(pc1, 8, w3.x); VR1(4); SB();
;                 PV1(1, w0); EX2(pc1, 10, w3.y); VR1(5); SB();
;                 PV1(2, w1); EX2(pc1, 12, w3.z); VR1(6); SB();
;                 PV1(3, w1); EX2(pc1, 14, w3.w); VR1(7); SB();
;                 lrun += sacc;
;                 PV1(4, w2); MASK_TILE(pn0, pn1, t + 1); SB();
;                 PV1(5, w2); SB();
;                 PV1(6, w3); SB();
;                 PV1(7, w3); rmn = rowmax32(pn0, pn1); if (!USE_NEGM) rmn -= mref; SB();
;     ...
;             if (hn) { STOREK(t & 1); STOREV((t + 1) & 1); }
;             __syncthreads();
.Lmla_p1_go:
	v_exp_f32_e32 v222, v82
	v_exp_f32_e32 v223, v83
	v_add_f32_e32 v164, 0, v222
	v_cvt_pk_bf16_f32 v206, v222, v223
	v_add_f32_e32 v164, v223, v164
	v_exp_f32_e32 v224, v84
	v_exp_f32_e32 v225, v85
	v_add_f32_e32 v164, v224, v164
	v_cvt_pk_bf16_f32 v207, v224, v225
	v_add_f32_e32 v164, v225, v164
	s_waitcnt lgkmcnt(3)
	v_mfma_f32_32x32x16_bf16 v[34:49], v[182:185], v[114:117], v[66:81]
	ds_read_b128 v[198:201], v229 offset:64
	v_exp_f32_e32 v222, v86
	v_exp_f32_e32 v223, v87
	v_add_f32_e32 v164, v222, v164
	v_cvt_pk_bf16_f32 v208, v222, v223
	v_add_f32_e32 v164, v223, v164
	s_waitcnt lgkmcnt(3)
	v_mfma_f32_32x32x16_bf16 v[50:65], v[186:189], v[114:117], v[66:81]
	ds_read_b128 v[182:185], v229 offset:6720
	v_exp_f32_e32 v224, v88
	v_exp_f32_e32 v225, v89
	v_add_f32_e32 v164, v224, v164
	v_cvt_pk_bf16_f32 v209, v224, v225
	v_add_f32_e32 v164, v225, v164
	s_waitcnt lgkmcnt(3)
	v_mfma_f32_32x32x16_bf16 v[34:49], v[190:193], v[118:121], v[34:49]
	ds_read_b128 v[186:189], v229 offset:96
	v_exp_f32_e32 v222, v90
	v_exp_f32_e32 v223, v91
	v_add_f32_e32 v164, v222, v164
	v_cvt_pk_bf16_f32 v210, v222, v223
	v_add_f32_e32 v164, v223, v164
	s_waitcnt lgkmcnt(3)
	v_mfma_f32_32x32x16_bf16 v[50:65], v[194:197], v[118:121], v[50:65]
	ds_read_b128 v[190:193], v229 offset:6752
	v_exp_f32_e32 v224, v92
	v_exp_f32_e32 v225, v93
	v_add_f32_e32 v164, v224, v164
	v_cvt_pk_bf16_f32 v211, v224, v225
	v_add_f32_e32 v164, v225, v164
	s_waitcnt lgkmcnt(3)
	v_mfma_f32_32x32x16_bf16 v[34:49], v[198:201], v[122:125], v[34:49]
	ds_read_b128 v[194:197], v229 offset:128
	v_exp_f32_e32 v222, v94
	v_exp_f32_e32 v223, v95
	v_add_f32_e32 v164, v222, v164
	v_cvt_pk_bf16_f32 v212, v222, v223
	v_add_f32_e32 v164, v223, v164
	s_waitcnt lgkmcnt(3)
	v_mfma_f32_32x32x16_bf16 v[50:65], v[182:185], v[122:125], v[50:65]
	ds_read_b128 v[198:201], v229 offset:6784
	v_exp_f32_e32 v224, v96
	v_exp_f32_e32 v225, v97
	v_add_f32_e32 v164, v224, v164
	v_cvt_pk_bf16_f32 v213, v224, v225
	v_add_f32_e32 v164, v225, v164
	s_waitcnt lgkmcnt(3)
	v_mfma_f32_32x32x16_bf16 v[34:49], v[186:189], v[126:129], v[34:49]
	ds_read_b128 v[182:185], v229 offset:160
	v_exp_f32_e32 v222, v98
	v_exp_f32_e32 v223, v99
	v_add_f32_e32 v164, v222, v164
	v_cvt_pk_bf16_f32 v214, v222, v223
	v_add_f32_e32 v164, v223, v164
	s_waitcnt lgkmcnt(3)
	v_mfma_f32_32x32x16_bf16 v[50:65], v[190:193], v[126:129], v[50:65]
	ds_read_b128 v[186:189], v229 offset:6816
	v_exp_f32_e32 v224, v100
	v_exp_f32_e32 v225, v101
	v_add_f32_e32 v164, v224, v164
	v_cvt_pk_bf16_f32 v215, v224, v225
	v_add_f32_e32 v164, v225, v164
	s_waitcnt lgkmcnt(3)
	v_mfma_f32_32x32x16_bf16 v[34:49], v[194:197], v[130:133], v[34:49]
	ds_read_b128 v[190:193], v228 offset:35840
	v_exp_f32_e32 v222, v102
	v_exp_f32_e32 v223, v103
	v_add_f32_e32 v164, v222, v164
	v_cvt_pk_bf16_f32 v216, v222, v223
	v_add_f32_e32 v164, v223, v164
	s_waitcnt lgkmcnt(3)
	v_mfma_f32_32x32x16_bf16 v[50:65], v[198:201], v[130:133], v[50:65]
	ds_read_b128 v[194:197], v228 offset:40448
	v_exp_f32_e32 v224, v104
	v_exp_f32_e32 v225, v105
	v_add_f32_e32 v164, v224, v164
	v_cvt_pk_bf16_f32 v217, v224, v225
	v_add_f32_e32 v164, v225, v164
	s_waitcnt lgkmcnt(3)
	v_mfma_f32_32x32x16_bf16 v[34:49], v[182:185], v[134:137], v[34:49]
	ds_read_b128 v[198:201], v228 offset:35872
	v_exp_f32_e32 v222, v106
	v_exp_f32_e32 v223, v107
	v_add_f32_e32 v164, v222, v164
	v_cvt_pk_bf16_f32 v218, v222, v223
	v_add_f32_e32 v164, v223, v164
	s_waitcnt lgkmcnt(3)
	v_mfma_f32_32x32x16_bf16 v[50:65], v[186:189], v[134:137], v[50:65]
	ds_read_b128 v[182:185], v228 offset:40480
	v_exp_f32_e32 v224, v108
	v_exp_f32_e32 v225, v109
	v_add_f32_e32 v164, v224, v164
	v_cvt_pk_bf16_f32 v219, v224, v225
	v_add_f32_e32 v164, v225, v164
	s_waitcnt lgkmcnt(3)
	v_mfma_f32_32x32x16_bf16 v[2:17], v[190:193], v[206:209], v[2:17]
	ds_read_b128 v[186:189], v228 offset:35904
	v_exp_f32_e32 v222, v110
	v_exp_f32_e32 v223, v111
	v_add_f32_e32 v164, v222, v164
	v_cvt_pk_bf16_f32 v220, v222, v223
	v_add_f32_e32 v164, v223, v164
	s_waitcnt lgkmcnt(3)
	v_mfma_f32_32x32x16_bf16 v[18:33], v[194:197], v[206:209], v[18:33]
	ds_read_b128 v[190:193], v228 offset:40512
	v_exp_f32_e32 v224, v112
	v_exp_f32_e32 v225, v113
	v_add_f32_e32 v164, v224, v164
	v_cvt_pk_bf16_f32 v221, v224, v225
	v_add_f32_e32 v164, v225, v164
	s_waitcnt lgkmcnt(3)
	v_mfma_f32_32x32x16_bf16 v[2:17], v[198:201], v[210:213], v[2:17]
	ds_read_b128 v[194:197], v228 offset:35936
	v_max3_f32 v224, v34, v35, v36
	v_max3_f32 v225, v50, v51, v52
	v_max3_f32 v224, v224, v37, v38
	s_waitcnt lgkmcnt(3)
	v_mfma_f32_32x32x16_bf16 v[18:33], v[182:185], v[210:213], v[18:33]
	ds_read_b128 v[198:201], v228 offset:40544
	v_max3_f32 v225, v225, v53, v54
	v_max3_f32 v224, v224, v39, v40
	v_max3_f32 v225, v225, v55, v56
	s_waitcnt lgkmcnt(3)
	v_mfma_f32_32x32x16_bf16 v[2:17], v[186:189], v[214:217], v[2:17]
	ds_read_b128 v[182:185], v229 offset:22528
	v_max3_f32 v224, v224, v41, v42
	v_max3_f32 v225, v225, v57, v58
	v_max3_f32 v224, v224, v43, v44
	s_add_i32 s0, s11, 4
	s_min_u32 s0, s0, s12
	s_add_i32 s0, s0, s10
	s_cmp_ge_i32 s0, s9
	s_cselect_b32 s1, s9, 0
	s_sub_i32 s19, s0, s1
	s_add_i32 s0, s11, 3
	s_min_u32 s0, s0, s12
	s_add_i32 s0, s0, s10
	s_cmp_ge_i32 s0, s9
	s_cselect_b32 s1, s9, 0
	s_sub_i32 s13, s0, s1
	s_waitcnt lgkmcnt(3)
	v_mfma_f32_32x32x16_bf16 v[18:33], v[190:193], v[214:217], v[18:33]
	ds_read_b128 v[186:189], v229 offset:29184
	v_max3_f32 v225, v225, v59, v60
	v_max3_f32 v224, v224, v45, v46
	v_max3_f32 v225, v225, v61, v62
	s_and_b64 vcc, exec, s[2:3]
	s_cbranch_vccz .Lmla_p1_w47
	s_waitcnt vmcnt(3)
	ds_write_b128 v176, v[160:163] offset:128
	ds_write_b128 v172, v[150:153]
	v_add_u32_e32 v222, 0xb000, v173
	ds_write_b128 v222, v[202:205] offset:35840
	v_lshl_add_u32 v222, s19, 12, v179
	global_load_dwordx4 v[160:163], v222, s[62:63]
	v_lshl_add_u32 v222, s19, 17, v178
	global_load_dwordx4 v[150:153], v222, s[52:53]
	v_lshl_add_u32 v222, s13, 7, v168
	global_load_dwordx4 v[202:205], v222, s[56:57]
	s_branch .Lmla_p1_join
.Lmla_p1_w47:
	s_waitcnt vmcnt(2)
	ds_write_b128 v172, v[150:153]
	v_add_u32_e32 v222, 0xb000, v173
	ds_write_b128 v222, v[202:205] offset:35840
	v_lshl_add_u32 v222, s19, 17, v178
	global_load_dwordx4 v[150:153], v222, s[52:53]
	v_lshl_add_u32 v222, s13, 7, v168
	global_load_dwordx4 v[202:205], v222, s[56:57]
.Lmla_p1_join:
	s_waitcnt lgkmcnt(5)
	v_mfma_f32_32x32x16_bf16 v[2:17], v[194:197], v[218:221], v[2:17]
	ds_read_b128 v[190:193], v229 offset:22560
	v_max3_f32 v224, v224, v47, v48
	v_max3_f32 v225, v225, v63, v64
	s_waitcnt lgkmcnt(5)
	v_mfma_f32_32x32x16_bf16 v[18:33], v[198:201], v[218:221], v[18:33]
	ds_read_b128 v[194:197], v229 offset:29216
	v_max3_f32 v224, v224, v49, v65
	v_max_f32_e32 v224, v224, v225
	v_mov_b32_e32 v225, v224
	v_add_f32_e32 v1, v1, v164
	s_add_i32 s11, s11, 1
	s_nop 0
	v_permlane32_swap_b32_e32 v224, v225
	s_cmp_eq_u32 s9, s11
	v_max_f32_e32 v167, v224, v225
	s_waitcnt lgkmcnt(2)
	s_barrier
	s_cbranch_scc1 .Lmla_exit_p1

; template <int VAR>
; __device__ __forceinline__ void attn_phase(LAS unsigned char* lds, const AttnP P, int vcu, int G, int wave_s) {
;     ...
;                 if (ND0 == 6) {
;                     KR1(0); KR1(1); KR1(2); KR1(3); SB();
;                     QK1(0, negm); EX2(pc0, 0, w0.x); KR1(4); SB();
;                     QK1(1, negm); EX2(pc0, 2, w0.y); KR1(5); SB();
;                     QK1(2, pn0); EX2(pc0, 4, w0.z); KR1(6); SB();
;                     QK1(3, pn1); EX2(pc0, 6, w0.w); KR1(7); SB();
;                     QK1(4, pn0); EX2(pc0, 8, w1.x); KR1(8); SB();
;                     QK1(5, pn1); EX2(pc0, 10, w1.y); KR1(9); SB();
;                     QK1(6, pn0); EX2(pc0, 12, w1.z); KR1(10); SB();
;                     QK1(7, pn1); EX2(pc0, 14, w1.w); KR1(11); SB();
;                     QK1(8, pn0); EX2(pc1, 0, w2.x); VR1(0); SB();
;                     QK1(9, pn1); EX2(pc1, 2, w2.y); VR1(1); SB();
;                     QK1(10, pn0); EX2(pc1, 4, w2.z); VR1(2); SB();
;                     QK1(11, pn1); EX2(pc1, 6, w2.w); VR1(3); SB();
;                 } else {
;                     KR1(0); KR1(1); KR1(2); KR1(3); SB();
;                     QK1(0, negm); EX2(pc0, 0, w0.x); EX2(pc0, 2, w0.y); KR1(4); SB();
;                     QK1(1, negm); EX2(pc0, 4, w0.z); EX2(pc0, 6, w0.w); KR1(5); SB();
;                     QK1(2, pn0); EX2(pc0, 8, w1.x); EX2(pc0, 10, w1.y); KR1(6); SB();
;                     QK1(3, pn1); EX2(pc0, 12, w1.z); EX2(pc0, 14, w1.w); KR1(7); SB();
;                     QK1(4, pn0); EX2(pc1, 0, w2.x); VR1(0); SB();
;                     QK1(5, pn1); EX2(pc1, 2, w2.y); VR1(1); SB();
;                     QK1(6, pn0); EX2(pc1, 4, w2.z); VR1(2); SB();
;                     QK1(7, pn1); EX2(pc1, 6, w2.w); VR1(3); SB();
;                 }
;                 PV1(0, w0); EX2(pc1, 8, w3.x); VR1(4); SB();
;                 PV1(1, w0); EX2(pc1, 10, w3.y); VR1(5); SB();
;                 PV1(2, w1); EX2(pc1, 12, w3.z); VR1(6); SB();
;                 PV1(3, w1); EX2(pc1, 14, w3.w); VR1(7); SB();
;                 lrun += sacc;
;                 PV1(4, w2); MASK_TILE(pn0, pn1, t + 1); SB();
;                 PV1(5, w2); SB();
;                 PV1(6, w3); SB();
;                 PV1(7, w3); rmn = rowmax32(pn0, pn1); if (!USE_NEGM) rmn -= mref; SB();
;     ...
;             if (hn) { STOREK(t & 1); STOREV((t + 1) & 1); }
;             __syncthreads();
.Lmla_p2_go:
	v_exp_f32_e32 v222, v34
	v_exp_f32_e32 v223, v35
	v_add_f32_e32 v164, 0, v222
	v_cvt_pk_bf16_f32 v206, v222, v223
	v_add_f32_e32 v164, v223, v164
	v_exp_f32_e32 v224, v36
	v_exp_f32_e32 v225, v37
	v_add_f32_e32 v164, v224, v164
	v_cvt_pk_bf16_f32 v207, v224, v225
	v_add_f32_e32 v164, v225, v164
	s_waitcnt lgkmcnt(3)
	v_mfma_f32_32x32x16_bf16 v[82:97], v[182:185], v[114:117], v[66:81]
	ds_read_b128 v[198:201], v229 offset:22592
	v_exp_f32_e32 v222, v38
	v_exp_f32_e32 v223, v39
	v_add_f32_e32 v164, v222, v164
	v_cvt_pk_bf16_f32 v208, v222, v223
	v_add_f32_e32 v164, v223, v164
	s_waitcnt lgkmcnt(3)
	v_mfma_f32_32x32x16_bf16 v[98:113], v[186:189], v[114:117], v[66:81]
	ds_read_b128 v[182:185], v229 offset:29248
	v_exp_f32_e32 v224, v40
	v_exp_f32_e32 v225, v41
	v_add_f32_e32 v164, v224, v164
	v_cvt_pk_bf16_f32 v209, v224, v225
	v_add_f32_e32 v164, v225, v164
	s_waitcnt lgkmcnt(3)
	v_mfma_f32_32x32x16_bf16 v[82:97], v[190:193], v[118:121], v[82:97]
	ds_read_b128 v[186:189], v229 offset:22624
	v_exp_f32_e32 v222, v42
	v_exp_f32_e32 v223, v43
	v_add_f32_e32 v164, v222, v164
	v_cvt_pk_bf16_f32 v210, v222, v223
	v_add_f32_e32 v164, v223, v164
	s_waitcnt lgkmcnt(3)
	v_mfma_f32_32x32x16_bf16 v[98:113], v[194:197], v[118:121], v[98:113]
	ds_read_b128 v[190:193], v229 offset:29280
	v_exp_f32_e32 v224, v44
	v_exp_f32_e32 v225, v45
	v_add_f32_e32 v164, v224, v164
	v_cvt_pk_bf16_f32 v211, v224, v225
	v_add_f32_e32 v164, v225, v164
	s_waitcnt lgkmcnt(3)
	v_mfma_f32_32x32x16_bf16 v[82:97], v[198:201], v[122:125], v[82:97]
	ds_read_b128 v[194:197], v229 offset:22656
	v_exp_f32_e32 v222, v46
	v_exp_f32_e32 v223, v47
	v_add_f32_e32 v164, v222, v164
	v_cvt_pk_bf16_f32 v212, v222, v223
	v_add_f32_e32 v164, v223, v164
	s_waitcnt lgkmcnt(3)
	v_mfma_f32_32x32x16_bf16 v[98:113], v[182:185], v[122:125], v[98:113]
	ds_read_b128 v[198:201], v229 offset:29312
	v_exp_f32_e32 v224, v48
	v_exp_f32_e32 v225, v49
	v_add_f32_e32 v164, v224, v164
	v_cvt_pk_bf16_f32 v213, v224, v225
	v_add_f32_e32 v164, v225, v164
	s_waitcnt lgkmcnt(3)
	v_mfma_f32_32x32x16_bf16 v[82:97], v[186:189], v[126:129], v[82:97]
	ds_read_b128 v[182:185], v229 offset:22688
	v_exp_f32_e32 v222, v50
	v_exp_f32_e32 v223, v51
	v_add_f32_e32 v164, v222, v164
	v_cvt_pk_bf16_f32 v214, v222, v223
	v_add_f32_e32 v164, v223, v164
	s_waitcnt lgkmcnt(3)
	v_mfma_f32_32x32x16_bf16 v[98:113], v[190:193], v[126:129], v[98:113]
	ds_read_b128 v[186:189], v229 offset:29344
	v_exp_f32_e32 v224, v52
	v_exp_f32_e32 v225, v53
	v_add_f32_e32 v164, v224, v164
	v_cvt_pk_bf16_f32 v215, v224, v225
	v_add_f32_e32 v164, v225, v164
	s_waitcnt lgkmcnt(3)
	v_mfma_f32_32x32x16_bf16 v[82:97], v[194:197], v[130:133], v[82:97]
	ds_read_b128 v[190:193], v181 offset:13312
	v_exp_f32_e32 v222, v54
	v_exp_f32_e32 v223, v55
	v_add_f32_e32 v164, v222, v164
	v_cvt_pk_bf16_f32 v216, v222, v223
	v_add_f32_e32 v164, v223, v164
	s_waitcnt lgkmcnt(3)
	v_mfma_f32_32x32x16_bf16 v[98:113], v[198:201], v[130:133], v[98:113]
	ds_read_b128 v[194:197], v181 offset:17920
	v_exp_f32_e32 v224, v56
	v_exp_f32_e32 v225, v57
	v_add_f32_e32 v164, v224, v164
	v_cvt_pk_bf16_f32 v217, v224, v225
	v_add_f32_e32 v164, v225, v164
	s_waitcnt lgkmcnt(3)
	v_mfma_f32_32x32x16_bf16 v[82:97], v[182:185], v[134:137], v[82:97]
	ds_read_b128 v[198:201], v181 offset:13344
	v_exp_f32_e32 v222, v58
	v_exp_f32_e32 v223, v59
	v_add_f32_e32 v164, v222, v164
	v_cvt_pk_bf16_f32 v218, v222, v223
	v_add_f32_e32 v164, v223, v164
	s_waitcnt lgkmcnt(3)
	v_mfma_f32_32x32x16_bf16 v[98:113], v[186:189], v[134:137], v[98:113]
	ds_read_b128 v[182:185], v181 offset:17952
	v_exp_f32_e32 v224, v60
	v_exp_f32_e32 v225, v61
	v_add_f32_e32 v164, v224, v164
	v_cvt_pk_bf16_f32 v219, v224, v225
	v_add_f32_e32 v164, v225, v164
	s_waitcnt lgkmcnt(3)
	v_mfma_f32_32x32x16_bf16 v[2:17], v[190:193], v[206:209], v[2:17]
	ds_read_b128 v[186:189], v181 offset:13376
	v_exp_f32_e32 v222, v62
	v_exp_f32_e32 v223, v63
	v_add_f32_e32 v164, v222, v164
	v_cvt_pk_bf16_f32 v220, v222, v223
	v_add_f32_e32 v164, v223, v164
	s_waitcnt lgkmcnt(3)
	v_mfma_f32_32x32x16_bf16 v[18:33], v[194:197], v[206:209], v[18:33]
	ds_read_b128 v[190:193], v181 offset:17984
	v_exp_f32_e32 v224, v64
	v_exp_f32_e32 v225, v65
	v_add_f32_e32 v164, v224, v164
	v_cvt_pk_bf16_f32 v221, v224, v225
	v_add_f32_e32 v164, v225, v164
	s_waitcnt lgkmcnt(3)
	v_mfma_f32_32x32x16_bf16 v[2:17], v[198:201], v[210:213], v[2:17]
	ds_read_b128 v[194:197], v181 offset:13408
	v_max3_f32 v224, v82, v83, v84
	v_max3_f32 v225, v98, v99, v100
	v_max3_f32 v224, v224, v85, v86
	s_waitcnt lgkmcnt(3)
	v_mfma_f32_32x32x16_bf16 v[18:33], v[182:185], v[210:213], v[18:33]
	ds_read_b128 v[198:201], v181 offset:18016
	v_max3_f32 v225, v225, v101, v102
	v_max3_f32 v224, v224, v87, v88
	v_max3_f32 v225, v225, v103, v104
	s_waitcnt lgkmcnt(3)
	v_mfma_f32_32x32x16_bf16 v[2:17], v[186:189], v[214:217], v[2:17]
	ds_read_b128 v[182:185], v174
	v_max3_f32 v224, v224, v89, v90
	v_max3_f32 v225, v225, v105, v106
	v_max3_f32 v224, v224, v91, v92
	s_add_i32 s0, s11, 4
	s_min_u32 s0, s0, s12
	s_add_i32 s0, s0, s10
	s_cmp_ge_i32 s0, s9
	s_cselect_b32 s1, s9, 0
	s_sub_i32 s19, s0, s1
	s_add_i32 s0, s11, 3
	s_min_u32 s0, s0, s12
	s_add_i32 s0, s0, s10
	s_cmp_ge_i32 s0, s9
	s_cselect_b32 s1, s9, 0
	s_sub_i32 s13, s0, s1
	s_waitcnt lgkmcnt(3)
	v_mfma_f32_32x32x16_bf16 v[18:33], v[190:193], v[214:217], v[18:33]
	ds_read_b128 v[186:189], v174 offset:6656
	v_max3_f32 v225, v225, v107, v108
	v_max3_f32 v224, v224, v93, v94
	v_max3_f32 v225, v225, v109, v110
	s_and_b64 vcc, exec, s[2:3]
	s_cbranch_vccz .Lmla_p2_w47
	s_waitcnt vmcnt(3)
	ds_write_b128 v176, v[138:141] offset:22656
	ds_write_b128 v172, v[146:149] offset:22528
	ds_write_b128 v173, v[142:145] offset:13312
	v_lshl_add_u32 v222, s19, 12, v179
	global_load_dwordx4 v[138:141], v222, s[62:63]
	v_lshl_add_u32 v222, s19, 17, v178
	global_load_dwordx4 v[146:149], v222, s[52:53]
	v_lshl_add_u32 v222, s13, 7, v168
	global_load_dwordx4 v[142:145], v222, s[56:57]
	s_branch .Lmla_p2_join
.Lmla_p2_w47:
	s_waitcnt vmcnt(2)
	ds_write_b128 v172, v[146:149] offset:22528
	ds_write_b128 v173, v[142:145] offset:13312
	v_lshl_add_u32 v222, s19, 17, v178
	global_load_dwordx4 v[146:149], v222, s[52:53]
	v_lshl_add_u32 v222, s13, 7, v168
	global_load_dwordx4 v[142:145], v222, s[56:57]
.Lmla_p2_join:
	s_waitcnt lgkmcnt(5)
	v_mfma_f32_32x32x16_bf16 v[2:17], v[194:197], v[218:221], v[2:17]
	ds_read_b128 v[190:193], v174 offset:32
	v_max3_f32 v224, v224, v95, v96
	v_max3_f32 v225, v225, v111, v112
	s_waitcnt lgkmcnt(5)
	v_mfma_f32_32x32x16_bf16 v[18:33], v[198:201], v[218:221], v[18:33]
	ds_read_b128 v[194:197], v174 offset:6688
	v_max3_f32 v224, v224, v97, v113
	v_max_f32_e32 v224, v224, v225
	v_mov_b32_e32 v225, v224
	v_add_f32_e32 v1, v1, v164
	s_add_i32 s11, s11, 1
	s_nop 0
	v_permlane32_swap_b32_e32 v224, v225
	s_cmp_eq_u32 s9, s11
	v_max_f32_e32 v167, v224, v225
	s_waitcnt lgkmcnt(2)
	s_barrier
	s_cbranch_scc1 .Lmla_exit_p2

; template <int VAR>
; __device__ __forceinline__ void attn_phase(LAS unsigned char* lds, const AttnP P, int vcu, int G, int wave_s) {
;     ...
;                 if (ND0 == 6) {
;                     KR1(0); KR1(1); KR1(2); KR1(3); SB();
;                     QK1(0, negm); EX2(pc0, 0, w0.x); KR1(4); SB();
;                     QK1(1, negm); EX2(pc0, 2, w0.y); KR1(5); SB();
;                     QK1(2, pn0); EX2(pc0, 4, w0.z); KR1(6); SB();
;                     QK1(3, pn1); EX2(pc0, 6, w0.w); KR1(7); SB();
;                     QK1(4, pn0); EX2(pc0, 8, w1.x); KR1(8); SB();
;                     QK1(5, pn1); EX2(pc0, 10, w1.y); KR1(9); SB();
;                     QK1(6, pn0); EX2(pc0, 12, w1.z); KR1(10); SB();
;                     QK1(7, pn1); EX2(pc0, 14, w1.w); KR1(11); SB();
;                     QK1(8, pn0); EX2(pc1, 0, w2.x); VR1(0); SB();
;                     QK1(9, pn1); EX2(pc1, 2, w2.y); VR1(1); SB();
;                     QK1(10, pn0); EX2(pc1, 4, w2.z); VR1(2); SB();
;                     QK1(11, pn1); EX2(pc1, 6, w2.w); VR1(3); SB();
;                 } else {
;                     KR1(0); KR1(1); KR1(2); KR1(3); SB();
;                     QK1(0, negm); EX2(pc0, 0, w0.x); EX2(pc0, 2, w0.y); KR1(4); SB();
;                     QK1(1, negm); EX2(pc0, 4, w0.z); EX2(pc0, 6, w0.w); KR1(5); SB();
;                     QK1(2, pn0); EX2(pc0, 8, w1.x); EX2(pc0, 10, w1.y); KR1(6); SB();
;                     QK1(3, pn1); EX2(pc0, 12, w1.z); EX2(pc0, 14, w1.w); KR1(7); SB();
;                     QK1(4, pn0); EX2(pc1, 0, w2.x); VR1(0); SB();
;                     QK1(5, pn1); EX2(pc1, 2, w2.y); VR1(1); SB();
;                     QK1(6, pn0); EX2(pc1, 4, w2.z); VR1(2); SB();
;                     QK1(7, pn1); EX2(pc1, 6, w2.w); VR1(3); SB();
;                 }
;                 PV1(0, w0); EX2(pc1, 8, w3.x); VR1(4); SB();
;                 PV1(1, w0); EX2(pc1, 10, w3.y); VR1(5); SB();
;                 PV1(2, w1); EX2(pc1, 12, w3.z); VR1(6); SB();
;                 PV1(3, w1); EX2(pc1, 14, w3.w); VR1(7); SB();
;                 lrun += sacc;
;                 PV1(4, w2); MASK_TILE(pn0, pn1, t + 1); SB();
;                 PV1(5, w2); SB();
;                 PV1(6, w3); SB();
;                 PV1(7, w3); rmn = rowmax32(pn0, pn1); if (!USE_NEGM) rmn -= mref; SB();
;     ...
;             if (hn) { STOREK(t & 1); STOREV((t + 1) & 1); }
;             __syncthreads();
.Lmla_p3_go:
	v_exp_f32_e32 v222, v82
	v_exp_f32_e32 v223, v83
	v_add_f32_e32 v164, 0, v222
	v_cvt_pk_bf16_f32 v206, v222, v223
	v_add_f32_e32 v164, v223, v164
	v_exp_f32_e32 v224, v84
	v_exp_f32_e32 v225, v85
	v_add_f32_e32 v164, v224, v164
	v_cvt_pk_bf16_f32 v207, v224, v225
	v_add_f32_e32 v164, v225, v164
	s_waitcnt lgkmcnt(3)
	v_mfma_f32_32x32x16_bf16 v[34:49], v[182:185], v[114:117], v[66:81]
	ds_read_b128 v[198:201], v174 offset:64
	v_exp_f32_e32 v222, v86
	v_exp_f32_e32 v223, v87
	v_add_f32_e32 v164, v222, v164
	v_cvt_pk_bf16_f32 v208, v222, v223
	v_add_f32_e32 v164, v223, v164
	s_waitcnt lgkmcnt(3)
	v_mfma_f32_32x32x16_bf16 v[50:65], v[186:189], v[114:117], v[66:81]
	ds_read_b128 v[182:185], v174 offset:6720
	v_exp_f32_e32 v224, v88
	v_exp_f32_e32 v225, v89
	v_add_f32_e32 v164, v224, v164
	v_cvt_pk_bf16_f32 v209, v224, v225
	v_add_f32_e32 v164, v225, v164
	s_waitcnt lgkmcnt(3)
	v_mfma_f32_32x32x16_bf16 v[34:49], v[190:193], v[118:121], v[34:49]
	ds_read_b128 v[186:189], v174 offset:96
	v_exp_f32_e32 v222, v90
	v_exp_f32_e32 v223, v91
	v_add_f32_e32 v164, v222, v164
	v_cvt_pk_bf16_f32 v210, v222, v223
	v_add_f32_e32 v164, v223, v164
	s_waitcnt lgkmcnt(3)
	v_mfma_f32_32x32x16_bf16 v[50:65], v[194:197], v[118:121], v[50:65]
	ds_read_b128 v[190:193], v174 offset:6752
	v_exp_f32_e32 v224, v92
	v_exp_f32_e32 v225, v93
	v_add_f32_e32 v164, v224, v164
	v_cvt_pk_bf16_f32 v211, v224, v225
	v_add_f32_e32 v164, v225, v164
	s_waitcnt lgkmcnt(3)
	v_mfma_f32_32x32x16_bf16 v[34:49], v[198:201], v[122:125], v[34:49]
	ds_read_b128 v[194:197], v174 offset:128
	v_exp_f32_e32 v222, v94
	v_exp_f32_e32 v223, v95
	v_add_f32_e32 v164, v222, v164
	v_cvt_pk_bf16_f32 v212, v222, v223
	v_add_f32_e32 v164, v223, v164
	s_waitcnt lgkmcnt(3)
	v_mfma_f32_32x32x16_bf16 v[50:65], v[182:185], v[122:125], v[50:65]
	ds_read_b128 v[198:201], v174 offset:6784
	v_exp_f32_e32 v224, v96
	v_exp_f32_e32 v225, v97
	v_add_f32_e32 v164, v224, v164
	v_cvt_pk_bf16_f32 v213, v224, v225
	v_add_f32_e32 v164, v225, v164
	s_waitcnt lgkmcnt(3)
	v_mfma_f32_32x32x16_bf16 v[34:49], v[186:189], v[126:129], v[34:49]
	ds_read_b128 v[182:185], v174 offset:160
	v_exp_f32_e32 v222, v98
	v_exp_f32_e32 v223, v99
	v_add_f32_e32 v164, v222, v164
	v_cvt_pk_bf16_f32 v214, v222, v223
	v_add_f32_e32 v164, v223, v164
	s_waitcnt lgkmcnt(3)
	v_mfma_f32_32x32x16_bf16 v[50:65], v[190:193], v[126:129], v[50:65]
	ds_read_b128 v[186:189], v174 offset:6816
	v_exp_f32_e32 v224, v100
	v_exp_f32_e32 v225, v101
	v_add_f32_e32 v164, v224, v164
	v_cvt_pk_bf16_f32 v215, v224, v225
	v_add_f32_e32 v164, v225, v164
	s_waitcnt lgkmcnt(3)
	v_mfma_f32_32x32x16_bf16 v[34:49], v[194:197], v[130:133], v[34:49]
	ds_read_b128 v[190:193], v181 offset:35840
	v_exp_f32_e32 v222, v102
	v_exp_f32_e32 v223, v103
	v_add_f32_e32 v164, v222, v164
	v_cvt_pk_bf16_f32 v216, v222, v223
	v_add_f32_e32 v164, v223, v164
	s_waitcnt lgkmcnt(3)
	v_mfma_f32_32x32x16_bf16 v[50:65], v[198:201], v[130:133], v[50:65]
	ds_read_b128 v[194:197], v181 offset:40448
	v_exp_f32_e32 v224, v104
	v_exp_f32_e32 v225, v105
	v_add_f32_e32 v164, v224, v164
	v_cvt_pk_bf16_f32 v217, v224, v225
	v_add_f32_e32 v164, v225, v164
	s_waitcnt lgkmcnt(3)
	v_mfma_f32_32x32x16_bf16 v[34:49], v[182:185], v[134:137], v[34:49]
	ds_read_b128 v[198:201], v181 offset:35872
	v_exp_f32_e32 v222, v106
	v_exp_f32_e32 v223, v107
	v_add_f32_e32 v164, v222, v164
	v_cvt_pk_bf16_f32 v218, v222, v223
	v_add_f32_e32 v164, v223, v164
	s_waitcnt lgkmcnt(3)
	v_mfma_f32_32x32x16_bf16 v[50:65], v[186:189], v[134:137], v[50:65]
	ds_read_b128 v[182:185], v181 offset:40480
	v_exp_f32_e32 v224, v108
	v_exp_f32_e32 v225, v109
	v_add_f32_e32 v164, v224, v164
	v_cvt_pk_bf16_f32 v219, v224, v225
	v_add_f32_e32 v164, v225, v164
	s_waitcnt lgkmcnt(3)
	v_mfma_f32_32x32x16_bf16 v[2:17], v[190:193], v[206:209], v[2:17]
	ds_read_b128 v[186:189], v181 offset:35904
	v_exp_f32_e32 v222, v110
	v_exp_f32_e32 v223, v111
	v_add_f32_e32 v164, v222, v164
	v_cvt_pk_bf16_f32 v220, v222, v223
	v_add_f32_e32 v164, v223, v164
	s_waitcnt lgkmcnt(3)
	v_mfma_f32_32x32x16_bf16 v[18:33], v[194:197], v[206:209], v[18:33]
	ds_read_b128 v[190:193], v181 offset:40512
	v_exp_f32_e32 v224, v112
	v_exp_f32_e32 v225, v113
	v_add_f32_e32 v164, v224, v164
	v_cvt_pk_bf16_f32 v221, v224, v225
	v_add_f32_e32 v164, v225, v164
	s_waitcnt lgkmcnt(3)
	v_mfma_f32_32x32x16_bf16 v[2:17], v[198:201], v[210:213], v[2:17]
	ds_read_b128 v[194:197], v181 offset:35936
	v_max3_f32 v224, v34, v35, v36
	v_max3_f32 v225, v50, v51, v52
	v_max3_f32 v224, v224, v37, v38
	s_waitcnt lgkmcnt(3)
	v_mfma_f32_32x32x16_bf16 v[18:33], v[182:185], v[210:213], v[18:33]
	ds_read_b128 v[198:201], v181 offset:40544
	v_max3_f32 v225, v225, v53, v54
	v_max3_f32 v224, v224, v39, v40
	v_max3_f32 v225, v225, v55, v56
	s_waitcnt lgkmcnt(3)
	v_mfma_f32_32x32x16_bf16 v[2:17], v[186:189], v[214:217], v[2:17]
	ds_read_b128 v[182:185], v174 offset:22528
	v_max3_f32 v224, v224, v41, v42
	v_max3_f32 v225, v225, v57, v58
	v_max3_f32 v224, v224, v43, v44
	s_add_i32 s0, s11, 4
	s_min_u32 s0, s0, s12
	s_add_i32 s0, s0, s10
	s_cmp_ge_i32 s0, s9
	s_cselect_b32 s1, s9, 0
	s_sub_i32 s19, s0, s1
	s_add_i32 s0, s11, 3
	s_min_u32 s0, s0, s12
	s_add_i32 s0, s0, s10
	s_cmp_ge_i32 s0, s9
	s_cselect_b32 s1, s9, 0
	s_sub_i32 s13, s0, s1
	s_waitcnt lgkmcnt(3)
	v_mfma_f32_32x32x16_bf16 v[18:33], v[190:193], v[214:217], v[18:33]
	ds_read_b128 v[186:189], v174 offset:29184
	v_max3_f32 v225, v225, v59, v60
	v_max3_f32 v224, v224, v45, v46
	v_max3_f32 v225, v225, v61, v62
	s_and_b64 vcc, exec, s[2:3]
	s_cbranch_vccz .Lmla_p3_w47
	s_waitcnt vmcnt(3)
	ds_write_b128 v176, v[160:163] offset:45184
	ds_write_b128 v172, v[150:153] offset:45056
	ds_write_b128 v173, v[202:205] offset:35840
	v_lshl_add_u32 v222, s19, 12, v179
	global_load_dwordx4 v[160:163], v222, s[62:63]
	v_lshl_add_u32 v222, s19, 17, v178
	global_load_dwordx4 v[150:153], v222, s[52:53]
	v_lshl_add_u32 v222, s13, 7, v168
	global_load_dwordx4 v[202:205], v222, s[56:57]
	s_branch .Lmla_p3_join
; #define STOREK(buf) do { LAS unsigned char* kb_ = lds + (buf) * ABUF; *(LAS u32x4*)(kb_ + (tid >> 3) * KP + (tid & 7) * 16) = kreg; \
;         if (VAR == 0 && tid < 256) *(LAS u32x4*)(kb_ + (tid >> 2) * KP + 128 + (tid & 3) * 16) = pereg; } while (0)
; #define STOREV(buf) do { *(LAS u32x4*)(lds + (buf) * ABUF + KT_BYTES + (tid >> 3) * VP + (tid & 7) * 16) = vreg; } while (0)
; #define SB() __builtin_amdgcn_sched_barrier(0)
; #define EX2(Pv, a, Wd) do { Pv[a] = __builtin_amdgcn_exp2f(Pv[a]); Pv[a + 1] = __builtin_amdgcn_exp2f(Pv[a + 1]); sacc += Pv[a]; sacc += Pv[a + 1]; Wd = cvtpk(Pv[a], Pv[a + 1]); } while (0)
; #define PV1(i, W) do { const bf16x8 pb_ = __builtin_bit_cast(bf16x8, W); if ((i) & 1) o1 = __builtin_amdgcn_mfma_f32_32x32x16_bf16(vf[i], pb_, o1, 0, 0, 0); else o0 = __builtin_amdgcn_mfma_f32_32x32x16_bf16(vf[i], pb_, o0, 0, 0, 0); } while (0)
; template <int VAR>
; __device__ __forceinline__ void attn_phase(LAS unsigned char* lds, const AttnP P, int vcu, int G, int wave_s) {
;     ...
;                 PV1(0, w0); EX2(pc1, 8, w3.x); VR1(4); SB();
;                 PV1(1, w0); EX2(pc1, 10, w3.y); VR1(5); SB();
;                 PV1(2, w1); EX2(pc1, 12, w3.z); VR1(6); SB();
;                 PV1(3, w1); EX2(pc1, 14, w3.w); VR1(7); SB();
;                 lrun += sacc;
;                 PV1(4, w2); MASK_TILE(pn0, pn1, t + 1); SB();
;                 PV1(5, w2); SB();
;                 PV1(6, w3); SB();
;                 PV1(7, w3); rmn = rowmax32(pn0, pn1); if (!USE_NEGM) rmn -= mref; SB();
;     ...
;             if (hn) { STOREK(t & 1); STOREV((t + 1) & 1); }
;             __syncthreads();
;             pc0 = pn0; pc1 = pn1; rmc = rmn; need_c = need_n;
.Lmla_p3_w47:
	s_waitcnt vmcnt(2)
	ds_write_b128 v172, v[150:153] offset:45056
	ds_write_b128 v173, v[202:205] offset:35840
	v_lshl_add_u32 v222, s19, 17, v178
	global_load_dwordx4 v[150:153], v222, s[52:53]
	v_lshl_add_u32 v222, s13, 7, v168
	global_load_dwordx4 v[202:205], v222, s[56:57]
.Lmla_p3_join:
	s_waitcnt lgkmcnt(5)
	v_mfma_f32_32x32x16_bf16 v[2:17], v[194:197], v[218:221], v[2:17]
	ds_read_b128 v[190:193], v174 offset:22560
	v_max3_f32 v224, v224, v47, v48
	v_max3_f32 v225, v225, v63, v64
	s_waitcnt lgkmcnt(5)
	v_mfma_f32_32x32x16_bf16 v[18:33], v[198:201], v[218:221], v[18:33]
	ds_read_b128 v[194:197], v174 offset:29216
	v_max3_f32 v224, v224, v49, v65
	v_max_f32_e32 v224, v224, v225
	v_mov_b32_e32 v225, v224
	v_add_f32_e32 v1, v1, v164
	s_add_i32 s11, s11, 1
	s_nop 0
	v_permlane32_swap_b32_e32 v224, v225
	s_cmp_eq_u32 s9, s11
	v_max_f32_e32 v167, v224, v225
	s_waitcnt lgkmcnt(2)
	s_barrier
	s_cbranch_scc1 .Lmla_exit_p3
	s_branch .Lmla_p0
.Lmla_exit_p0:
	s_setprio 0
	v_mov_b64_e32 v[34:35], v[82:83]
	v_mov_b64_e32 v[36:37], v[84:85]
	v_mov_b64_e32 v[38:39], v[86:87]
	v_mov_b64_e32 v[40:41], v[88:89]
	v_mov_b64_e32 v[42:43], v[90:91]
	v_mov_b64_e32 v[44:45], v[92:93]
	v_mov_b64_e32 v[46:47], v[94:95]
	v_mov_b64_e32 v[48:49], v[96:97]
	v_mov_b64_e32 v[50:51], v[98:99]
	v_mov_b64_e32 v[52:53], v[100:101]
	v_mov_b64_e32 v[54:55], v[102:103]
	v_mov_b64_e32 v[56:57], v[104:105]
	v_mov_b64_e32 v[58:59], v[106:107]
	v_mov_b64_e32 v[60:61], v[108:109]
	v_mov_b64_e32 v[62:63], v[110:111]
	v_mov_b64_e32 v[64:65], v[112:113]
	v_mov_b32_e32 v82, v167
	s_mov_b32 s11, 0x5800
	s_waitcnt vmcnt(0) lgkmcnt(0)
	s_branch .LBB0_1185
.Lmla_exit_p1:
	s_setprio 0
	v_mov_b32_e32 v82, v167
	s_mov_b32 s11, 0xb000
	s_waitcnt vmcnt(0) lgkmcnt(0)
	s_branch .LBB0_1185
.Lmla_exit_p2:
	s_setprio 0
	v_mov_b64_e32 v[34:35], v[82:83]
	v_mov_b64_e32 v[36:37], v[84:85]
	v_mov_b64_e32 v[38:39], v[86:87]
	v_mov_b64_e32 v[40:41], v[88:89]
	v_mov_b64_e32 v[42:43], v[90:91]
	v_mov_b64_e32 v[44:45], v[92:93]
	v_mov_b64_e32 v[46:47], v[94:95]
	v_mov_b64_e32 v[48:49], v[96:97]
	v_mov_b64_e32 v[50:51], v[98:99]
	v_mov_b64_e32 v[52:53], v[100:101]
	v_mov_b64_e32 v[54:55], v[102:103]
	v_mov_b64_e32 v[56:57], v[104:105]
	v_mov_b64_e32 v[58:59], v[106:107]
	v_mov_b64_e32 v[60:61], v[108:109]
	v_mov_b64_e32 v[62:63], v[110:111]
	v_mov_b64_e32 v[64:65], v[112:113]
	v_mov_b32_e32 v82, v167
	s_mov_b32 s11, 0x10800
	s_waitcnt vmcnt(0) lgkmcnt(0)
	s_branch .LBB0_1185
.Lmla_exit_p3:
	s_setprio 0
	v_mov_b32_e32 v82, v167
	s_mov_b32 s11, 0x0
	s_waitcnt vmcnt(0) lgkmcnt(0)
	s_branch .LBB0_1185

; template <int VAR>
; __device__ __forceinline__ void attn_phase(LAS unsigned char* lds, const AttnP P, int vcu, int G, int wave_s) {
;     ...
;             if (need_c && __any(rmc > THR)) {
;                 const float dl = __builtin_fmaxf(rmc, 0.f), f = __builtin_amdgcn_exp2f(-dl);
;                 mref += dl; lrun *= f;
; #pragma unroll
;                 for (int r = 0; r < 16; ++r) { if (USE_NEGM) { pc0[r] -= dl; pc1[r] -= dl; negm[r] = -mref; } o0[r] *= f; o1[r] *= f; }
;             }
.Lmla_p1_resc:
	v_max_f32_e32 v224, v167, v167
	v_max_f32_e32 v224, 0, v224
	v_exp_f32_e64 v225, -v224
	v_add_f32_e32 v180, v180, v224
	v_sub_f32_e32 v82, v82, v224
	v_sub_f32_e32 v83, v83, v224
	v_sub_f32_e32 v84, v84, v224
	v_sub_f32_e32 v85, v85, v224
	v_sub_f32_e32 v86, v86, v224
	v_sub_f32_e32 v87, v87, v224
	v_sub_f32_e32 v88, v88, v224
	v_sub_f32_e32 v89, v89, v224
	v_sub_f32_e32 v90, v90, v224
	v_sub_f32_e32 v91, v91, v224
	v_sub_f32_e32 v92, v92, v224
	v_sub_f32_e32 v93, v93, v224
	v_sub_f32_e32 v94, v94, v224
	v_sub_f32_e32 v95, v95, v224
	v_sub_f32_e32 v96, v96, v224
	v_sub_f32_e32 v97, v97, v224
	v_sub_f32_e32 v98, v98, v224
	v_sub_f32_e32 v99, v99, v224
	v_sub_f32_e32 v100, v100, v224
	v_sub_f32_e32 v101, v101, v224
	v_sub_f32_e32 v102, v102, v224
	v_sub_f32_e32 v103, v103, v224
	v_sub_f32_e32 v104, v104, v224
	v_sub_f32_e32 v105, v105, v224
	v_sub_f32_e32 v106, v106, v224
	v_sub_f32_e32 v107, v107, v224
	v_sub_f32_e32 v108, v108, v224
	v_sub_f32_e32 v109, v109, v224
	v_sub_f32_e32 v110, v110, v224
	v_sub_f32_e32 v111, v111, v224
	v_sub_f32_e32 v112, v112, v224
	v_sub_f32_e32 v113, v113, v224
	v_mul_f32_e32 v2, v2, v225
	v_mul_f32_e32 v3, v3, v225
	v_mul_f32_e32 v4, v4, v225
	v_mul_f32_e32 v5, v5, v225
	v_mul_f32_e32 v6, v6, v225
	v_mul_f32_e32 v7, v7, v225
	v_mul_f32_e32 v8, v8, v225
	v_mul_f32_e32 v9, v9, v225
	v_mul_f32_e32 v10, v10, v225
	v_mul_f32_e32 v11, v11, v225
	v_mul_f32_e32 v12, v12, v225
	v_mul_f32_e32 v13, v13, v225
	v_mul_f32_e32 v14, v14, v225
	v_mul_f32_e32 v15, v15, v225
	v_mul_f32_e32 v16, v16, v225
	v_mul_f32_e32 v17, v17, v225
	v_mul_f32_e32 v18, v18, v225
	v_mul_f32_e32 v19, v19, v225
	v_mul_f32_e32 v20, v20, v225
	v_mul_f32_e32 v21, v21, v225
	v_mul_f32_e32 v22, v22, v225
	v_mul_f32_e32 v23, v23, v225
	v_mul_f32_e32 v24, v24, v225
	v_mul_f32_e32 v25, v25, v225
	v_mul_f32_e32 v26, v26, v225
	v_mul_f32_e32 v27, v27, v225
	v_mul_f32_e32 v28, v28, v225
	v_mul_f32_e32 v29, v29, v225
	v_mul_f32_e32 v30, v30, v225
	v_mul_f32_e32 v31, v31, v225
	v_mul_f32_e32 v32, v32, v225
	v_mul_f32_e32 v33, v33, v225
	v_mul_f32_e32 v1, v1, v225
	v_xor_b32_e32 v66, 0x80000000, v180
	v_mov_b32_e32 v67, v66
	v_mov_b32_e32 v68, v66
	v_mov_b32_e32 v69, v66
	v_mov_b32_e32 v70, v66
	v_mov_b32_e32 v71, v66
	v_mov_b32_e32 v72, v66
	v_mov_b32_e32 v73, v66
	v_mov_b32_e32 v74, v66
	v_mov_b32_e32 v75, v66
	v_mov_b32_e32 v76, v66
	v_mov_b32_e32 v77, v66
	v_mov_b32_e32 v78, v66
	v_mov_b32_e32 v79, v66
	v_mov_b32_e32 v80, v66
	v_mov_b32_e32 v81, v66
	s_branch .Lmla_p1_go
.Lmla_p2_resc:
	v_max_f32_e32 v224, v167, v167
	v_max_f32_e32 v224, 0, v224
	v_exp_f32_e64 v225, -v224
	v_add_f32_e32 v180, v180, v224
	v_sub_f32_e32 v34, v34, v224
	v_sub_f32_e32 v35, v35, v224
	v_sub_f32_e32 v36, v36, v224
	v_sub_f32_e32 v37, v37, v224
	v_sub_f32_e32 v38, v38, v224
	v_sub_f32_e32 v39, v39, v224
	v_sub_f32_e32 v40, v40, v224
	v_sub_f32_e32 v41, v41, v224
	v_sub_f32_e32 v42, v42, v224
	v_sub_f32_e32 v43, v43, v224
	v_sub_f32_e32 v44, v44, v224
	v_sub_f32_e32 v45, v45, v224
	v_sub_f32_e32 v46, v46, v224
	v_sub_f32_e32 v47, v47, v224
	v_sub_f32_e32 v48, v48, v224
	v_sub_f32_e32 v49, v49, v224
	v_sub_f32_e32 v50, v50, v224
	v_sub_f32_e32 v51, v51, v224
	v_sub_f32_e32 v52, v52, v224
	v_sub_f32_e32 v53, v53, v224
	v_sub_f32_e32 v54, v54, v224
	v_sub_f32_e32 v55, v55, v224
	v_sub_f32_e32 v56, v56, v224
	v_sub_f32_e32 v57, v57, v224
	v_sub_f32_e32 v58, v58, v224
	v_sub_f32_e32 v59, v59, v224
	v_sub_f32_e32 v60, v60, v224
	v_sub_f32_e32 v61, v61, v224
	v_sub_f32_e32 v62, v62, v224
	v_sub_f32_e32 v63, v63, v224
	v_sub_f32_e32 v64, v64, v224
	v_sub_f32_e32 v65, v65, v224
	v_mul_f32_e32 v2, v2, v225
	v_mul_f32_e32 v3, v3, v225
	v_mul_f32_e32 v4, v4, v225
	v_mul_f32_e32 v5, v5, v225
	v_mul_f32_e32 v6, v6, v225
	v_mul_f32_e32 v7, v7, v225
	v_mul_f32_e32 v8, v8, v225
	v_mul_f32_e32 v9, v9, v225
	v_mul_f32_e32 v10, v10, v225
	v_mul_f32_e32 v11, v11, v225
	v_mul_f32_e32 v12, v12, v225
	v_mul_f32_e32 v13, v13, v225
	v_mul_f32_e32 v14, v14, v225
	v_mul_f32_e32 v15, v15, v225
	v_mul_f32_e32 v16, v16, v225
	v_mul_f32_e32 v17, v17, v225
	v_mul_f32_e32 v18, v18, v225
	v_mul_f32_e32 v19, v19, v225
	v_mul_f32_e32 v20, v20, v225
	v_mul_f32_e32 v21, v21, v225
	v_mul_f32_e32 v22, v22, v225
	v_mul_f32_e32 v23, v23, v225
	v_mul_f32_e32 v24, v24, v225
	v_mul_f32_e32 v25, v25, v225
	v_mul_f32_e32 v26, v26, v225
	v_mul_f32_e32 v27, v27, v225
	v_mul_f32_e32 v28, v28, v225
	v_mul_f32_e32 v29, v29, v225
	v_mul_f32_e32 v30, v30, v225
	v_mul_f32_e32 v31, v31, v225
	v_mul_f32_e32 v32, v32, v225
	v_mul_f32_e32 v33, v33, v225
	v_mul_f32_e32 v1, v1, v225
	v_xor_b32_e32 v66, 0x80000000, v180
	v_mov_b32_e32 v67, v66
	v_mov_b32_e32 v68, v66
	v_mov_b32_e32 v69, v66
	v_mov_b32_e32 v70, v66
	v_mov_b32_e32 v71, v66
	v_mov_b32_e32 v72, v66
	v_mov_b32_e32 v73, v66
	v_mov_b32_e32 v74, v66
	v_mov_b32_e32 v75, v66
	v_mov_b32_e32 v76, v66
	v_mov_b32_e32 v77, v66
	v_mov_b32_e32 v78, v66
	v_mov_b32_e32 v79, v66
	v_mov_b32_e32 v80, v66
	v_mov_b32_e32 v81, v66
	s_branch .Lmla_p2_go
